# grid barrier: acquire invalidate moved to wave 1 (off thread 0's atomic chain, leader inv removed) + redundant mout acquire inv removed
# baseline (speedup 1.0000x reference)
; __device__ __forceinline__ unsigned xb_add(unsigned* p, unsigned v) { return __hip_atomic_fetch_add(p, v, __ATOMIC_RELAXED, __HIP_MEMORY_SCOPE_AGENT); }
; __device__ __forceinline__ void xcd_barrier(const XcdBarrier& b) {
;     ...
;             __builtin_amdgcn_fence(__ATOMIC_ACQUIRE, "agent");
;             xb_add(&bar[XB_XGEN(b.x)], 1u);
;             asm volatile("s_waitcnt vmcnt(0)" ::: "memory");
.LBB0_9:
	s_or_b64 exec, exec, s[2:3]
	v_readlane_b32 s2, v252, 5
	v_readlane_b32 s3, v252, 6
	s_waitcnt vmcnt(0)
	s_nop 0
	s_nop 2
	global_atomic_add v1, v240, s[2:3]
	s_waitcnt vmcnt(0)

; #define VM_WAIT() asm volatile("s_waitcnt vmcnt(0)" ::: "memory")
; __device__ __forceinline__ void mlstm_out_loop(unsigned char* ws, h16* Y, const float* ghead  , int u  , const int o_mout, const int o_end, const int ntc, const bool ctx_out, ...
;     ...
;             if (wid == 0) { unsigned sp = 0; for (;;) { const unsigned f0 = __hip_atomic_load(chain + 64 * lane, RLX_AGENT), f1 = __hip_atomic_load(chain + 64 * (lane + 64), RLX_AGENT);
;                     if (__all(f0 != 0u && f1 != 0u)) break; __builtin_amdgcn_s_sleep(8); if (++sp > (1u << 20)) break; }
;                 __builtin_amdgcn_fence(__ATOMIC_ACQUIRE, "agent"); VM_WAIT(); if (lane == 0) *acq = 1u; }
.LBB0_407:
	s_nop 0
	s_waitcnt vmcnt(0)
	s_and_saveexec_b64 s[6:7], s[42:43]
	v_mov_b32_e32 v2, s82
	ds_write_b32 v2, v240
	s_or_b64 exec, exec, s[6:7]

; __device__ __forceinline__ unsigned xb_ld(unsigned* p)              { return __hip_atomic_load(p, __ATOMIC_RELAXED, __HIP_MEMORY_SCOPE_AGENT); }
; __device__ __forceinline__ unsigned xb_add(unsigned* p, unsigned v) { return __hip_atomic_fetch_add(p, v, __ATOMIC_RELAXED, __HIP_MEMORY_SCOPE_AGENT); }
; #define XB_SPIN(cond, bar) do { unsigned _sp = 0; while (cond) { __builtin_amdgcn_s_sleep(1); \
;     if ((++_sp & 255u) == 0u) { if (xb_ld(&(bar)[XB_TMO])) break; if (_sp > XB_SPIN_CAP) { atomicAdd(&(bar)[XB_TMO], 1u); break; } } } } while (0)
; __device__ __forceinline__ void xcd_barrier(const XcdBarrier& b) {
;     asm volatile("s_waitcnt vmcnt(0)" ::: "memory");
;     __syncthreads();
;     if (threadIdx.x == 0) {
;         unsigned* bar = b.bar;
;         __builtin_amdgcn_s_waitcnt(0);
;         unsigned nloc = b.st[0], nx = b.st[1];
;         if (nloc == 0u) { xcd_barrier_complete(bar, b.x, nloc, nx); b.st[0] = nloc; b.st[1] = nx; }
;         const unsigned old = xb_add(&bar[XB_XSUB(b.x)], 1u);
;         const unsigned gen = old / nloc;
;         if (old + 1u == (gen + 1u) * nloc) {
;             __builtin_amdgcn_fence(__ATOMIC_RELEASE, "agent");
;             asm volatile("s_waitcnt vmcnt(0)" ::: "memory");
;             const unsigned og = xb_add(&bar[XB_TOP], 1u);
;             const unsigned tg = og / nx;
;             if (og + 1u == (tg + 1u) * nx) xb_add(&bar[XB_TOPGEN], 1u);
;             else XB_SPIN(xb_ld(&bar[XB_TOPGEN]) == tg, bar);
;             __builtin_amdgcn_fence(__ATOMIC_ACQUIRE, "agent");
;             xb_add(&bar[XB_XGEN(b.x)], 1u);
;             asm volatile("s_waitcnt vmcnt(0)" ::: "memory");
;         } else {
;             XB_SPIN(xb_ld(&bar[XB_XGEN(b.x)]) == gen, bar);
;             __builtin_amdgcn_fence(__ATOMIC_ACQUIRE, "agent");
;             asm volatile("s_waitcnt vmcnt(0)" ::: "memory");
;         }
;     }
;     __syncthreads();
.LBB0_795:
	s_waitcnt vmcnt(0)
	s_waitcnt vmcnt(0) lgkmcnt(0)
	s_barrier
	s_mov_b64 s[0:1], exec
	v_readlane_b32 s2, v252, 26
	v_readlane_b32 s3, v252, 27
	s_and_b64 s[2:3], s[0:1], s[2:3]
	s_mov_b64 exec, s[2:3]
	s_cbranch_execnz .LBB0_796
	v_readlane_b32 s2, v252, 47
	s_nop 3
	s_cmp_lg_u32 s2, 1
	s_cbranch_scc1 .Lgb_noinv
	s_mov_b64 exec, s[0:1]
	buffer_inv sc1
	s_waitcnt vmcnt(0)
.Lgb_noinv:
	s_getpc_b64 s[98:99]
